# in_proj bias folded into accumulator init with prefetch; epilogue has no loads or drain
# speedup vs baseline: 1.0036x; 1.0036x over previous
; #define PG8_STAGE(bufoff, gbase, voff) do { _Pragma("unroll") for (int _i = 0; _i < 2; ++_i) \
;         __builtin_amdgcn_global_load_lds((const unsigned*)((const char*)(gbase) + (voff)[_i]), (LAS unsigned*)(lds + (bufoff) + ldsw + _i * 8192), 16, 0, 0); } while (0)
; #define PG8_BAR __builtin_amdgcn_s_barrier()
; template <class Epi, class Sched>
; __device__ __forceinline__ void gemm_phase(LAS unsigned char* lds, const Gemm g, const Sched& S, const Epi& E) {
;     ...
;     for (int i = 0; i < 2; ++i) { int R, C; stage_rc(tid * 16 + i * 8192, R, C); const int Rb = Epi::PERM ? (64 * (R >> 5) + perm32(R & 31)) : R;
;         voffA[i] = g.apair ? (unsigned)((R >> 1) * 2 * g.lda + (C >> 5) * 64 + (R & 1) * 32 + (C & 31)) * 2u : (unsigned)(R * g.lda + C) * 2u; voffB[i] = (unsigned)(Rb * g.ldb + C) * 2u; }
;     const size_t kstep = (size_t)(BK * 2), kstepA = g.apair ? 2 * kstep : kstep;
;     const size_t hA = (size_t)HALF * g.lda * 2, hB = (size_t)(Epi::PERM ? BJ : HALF) * g.ldb * 2;
;     const size_t tA = 2 * hA, tB = (size_t)BM * g.ldb * 2;
;     const unsigned ldsw = (unsigned)wid * 1024u;
;     const int aoff = lds_byte(wr * 64 + fr, fq * 8), boff = lds_byte(wc * 32 + fr, fq * 8);
;     ...
;     Unit cur, nxt; int ui = 0;
;     if (!S.next(0, cur)) return;
;     f32x4 acc[2][2][4][2];
; #pragma unroll
;     for (int a = 0; a < 2; ++a)
; #pragma unroll
;         for (int b = 0; b < 2; ++b)
; #pragma unroll
;             for (int m = 0; m < 4; ++m)
; #pragma unroll
;                 for (int n = 0; n < 2; ++n) acc[a][b][m][n] = (f32x4){0.f, 0.f, 0.f, 0.f};
;     bf16x8 At[4][2], B0[2][2], B1[2][2];
;     const char* cA = (const char*)g.A + (size_t)cur.pm * tA + (size_t)cur.k0 * 2; const char* cB = (const char*)g.Bt + (size_t)cur.pn * tB + (size_t)cur.k0 * 2;
;     PG8_STAGE(PG8_SB(0, 0), cB, voffB); PG8_STAGE(PG8_SB(0, 1), cB + hB, voffB); PG8_STAGE(PG8_SA(0, 0), cA, voffA); PG8_STAGE(PG8_SA(0, 1), cA + hA, voffA);
;     if (wr == 1) PG8_BAR;
;     PG8_WAIT_V(2); PG8_BAR;
;     PG8_STAGE(PG8_SB(1, 0), cB + kstep, voffB); PG8_STAGE(PG8_SA(1, 0), cA + kstepA, voffA); PG8_STAGE(PG8_SB(1, 1), cB + hB + kstep, voffB);
;     PG8_WAIT_V(6); PG8_BAR;
;     __device__ __forceinline__ void operator()(Acc& acc, const Unit& u, int wr, int wc, int fr, int fq) const {
;     ...
;             for (int n = 0; n < 2; ++n) bv[bj][n] = *(const f32x4*)(bias + colb + bj * BJ + 4 * n);
.LBB0_253:
	v_lshrrev_b32_e32 v18, 1, v6
	v_and_b32_e32 v18, 24, v18
	v_and_b32_e32 v13, 15, v6
	v_lshlrev_b32_e32 v19, 1, v18
	v_lshlrev_b32_e32 v20, 2, v6
	v_readlane_b32 s80, v249, 9
	s_and_b32 s10, s3, 3
	v_lshl_or_b32 v19, v13, 6, v19
	s_lshl_b32 s3, s1, 13
	v_and_b32_e32 v20, 32, v20
	v_readlane_b32 s84, v249, 13
	v_readlane_b32 s85, v249, 14
	v_bitop3_b32 v21, v19, s3, v20 bitop3:0xde
	s_lshl_b32 s3, s10, 12
	v_readlane_b32 s86, v249, 15
	v_readlane_b32 s87, v249, 16
	v_readlane_b32 s88, v249, 17
	v_readlane_b32 s89, v249, 18
	s_mov_b64 s[12:13], s[84:85]
	v_bitop3_b32 v175, v19, s3, v20 bitop3:0xde
	s_mul_hi_u32 s3, s2, 0xa000
	s_mul_i32 s2, s2, 0xa000
	s_mov_b64 s[14:15], s[86:87]
	v_readlane_b32 s18, v253, 36
	s_add_u32 s8, s14, s2
	v_mov_b32_e32 v165, v99
	v_readlane_b32 s19, v253, 37
	s_addc_u32 s9, s15, s3
	s_add_i32 m0, s35, 0x18000
	v_lshl_add_u64 v[2:3], v[2:3], 0, s[76:77]
	v_lshl_add_u64 v[14:15], s[18:19], 0, v[164:165]
	v_mov_b32_e32 v161, v99
	s_waitcnt vmcnt(2)
	s_barrier
	global_load_lds_dwordx4 v[2:3], off
	v_lshl_add_u64 v[2:3], v[4:5], 0, s[76:77]
	s_add_i32 m0, s35, 0x1a000
	s_add_i32 s39, s35, 0x8000
	s_add_i32 s40, s35, 0xa000
	v_lshl_add_u64 v[16:17], s[18:19], 0, v[160:161]
	global_load_lds_dwordx4 v[2:3], off
	v_lshl_add_u64 v[2:3], v[14:15], 0, s[76:77]
	s_mov_b32 m0, s39
	s_add_u32 s2, s22, 0x20080
	global_load_lds_dwordx4 v[2:3], off
	v_lshl_add_u64 v[2:3], v[16:17], 0, s[76:77]
	s_mov_b32 m0, s40
	s_addc_u32 s3, s23, 0
	global_load_lds_dwordx4 v[2:3], off
	s_add_i32 m0, s35, 0x1c000
	v_lshl_add_u64 v[2:3], s[2:3], 0, v[162:163]
	global_load_lds_dwordx4 v[2:3], off
	v_lshl_add_u64 v[2:3], s[2:3], 0, v[158:159]
	s_add_i32 m0, s35, 0x1e000
	s_cmpk_lt_u32 s0, 0x100
	global_load_lds_dwordx4 v[2:3], off
	v_lshl_or_b32 v174, s1, 6, v13
	s_cselect_b64 s[12:13], -1, 0
	s_lshl_b32 s41, s1, 1
	v_readlane_b32 s0, v251, 44
	v_lshlrev_b32_e32 v98, 5, v13
	v_readlane_b32 s1, v251, 45
	v_readlane_b32 s90, v249, 19
	v_readlane_b32 s91, v249, 20
	v_lshl_add_u64 v[2:3], s[0:1], 0, v[98:99]
	v_and_b32_e32 v98, 16, v6
	v_lshl_add_u64 v[166:167], v[2:3], 0, v[98:99]
	v_lshlrev_b32_e32 v2, 15, v11
	v_and_b32_e32 v2, 0xffff0000, v2
	v_lshl_add_u32 v2, v10, 12, v2
	v_and_b32_e32 v3, 1, v11
	v_lshl_or_b32 v2, v3, 6, v2
	v_lshl_add_u32 v168, v12, 1, v2
	v_lshlrev_b32_e32 v2, 15, v7
	v_and_b32_e32 v2, 0xffff0000, v2
	v_lshl_add_u32 v2, v8, 12, v2
	v_and_b32_e32 v3, 1, v7
	v_readlane_b32 s92, v249, 21
	v_readlane_b32 s93, v249, 22
	v_readlane_b32 s94, v249, 23
	v_readlane_b32 s95, v249, 24
	s_waitcnt vmcnt(6)
	v_lshl_or_b32 v2, v3, 6, v2
	v_mov_b32_e32 v98, v99
	v_lshl_add_u32 v170, v9, 1, v2
	v_mov_b32_e32 v100, v99
	v_mov_b32_e32 v101, v99
	v_mov_b64_e32 v[2:3], v[98:99]
	v_readlane_b32 s0, v253, 32
	v_readlane_b32 s50, v250, 25
	v_readlane_b32 s90, v254, 9
	v_readlane_b32 s92, v254, 11
	v_readlane_b32 s94, v254, 13
	s_mov_b64 s[16:17], s[88:89]
	s_add_i32 s41, s41, 0xfffd0000
	v_lshl_or_b32 v176, s10, 6, v18
	v_mov_b32_e32 v169, v99
	v_mov_b32_e32 v171, v99
	s_mov_b32 s42, 0
	v_add_u32_e32 v177, 0, v21
	v_mov_b64_e32 v[4:5], v[100:101]
	v_readlane_b32 s10, v252, 63
	s_mov_b32 s43, s0
	s_mov_b64 s[2:3], s[18:19]
	v_readlane_b32 s51, v250, 26
	v_readlane_b32 s52, v250, 31
	v_readlane_b32 s91, v254, 10
	v_readlane_b32 s93, v254, 12
	v_readlane_b32 s95, v254, 14
	v_readlane_b32 s53, v251, 40
	s_movk_i32 s55, 0x281
	s_mov_b32 s72, 0x43800000
	v_readlane_b32 s81, v249, 10
	v_readlane_b32 s82, v249, 11
	v_readlane_b32 s83, v249, 12
	s_barrier
	v_readlane_b32 s1, v253, 33
	v_lshl_or_b32 v210, s10, 8, v176
	v_mov_b32_e32 v211, 0
	v_lshl_add_u64 v[210:211], v[210:211], 2, s[8:9]
	global_load_dwordx4 v[194:197], v[210:211], off
	global_load_dwordx4 v[198:201], v[210:211], off offset:16
	global_load_dwordx4 v[202:205], v[210:211], off offset:128
	global_load_dwordx4 v[206:209], v[210:211], off offset:144
	s_waitcnt vmcnt(0)
	s_branch .LBB0_256

; #define PG8_STAGE(bufoff, gbase, voff) do { _Pragma("unroll") for (int _i = 0; _i < 2; ++_i) \
;         __builtin_amdgcn_global_load_lds((const unsigned*)((const char*)(gbase) + (voff)[_i]), (LAS unsigned*)(lds + (bufoff) + ldsw + _i * 8192), 16, 0, 0); } while (0)
; #define PG8_WAIT_V(n) asm volatile("s_waitcnt vmcnt(" #n ")" ::: "memory")
; #define PG8_BAR __builtin_amdgcn_s_barrier()
; template <class Epi, class Sched>
; __device__ __forceinline__ void gemm_phase(LAS unsigned char* lds, const Gemm g, const Sched& S, const Epi& E) {
;     ...
;     f32x4 acc[2][2][4][2];
; #pragma unroll
;     for (int a = 0; a < 2; ++a)
; #pragma unroll
;         for (int b = 0; b < 2; ++b)
; #pragma unroll
;             for (int m = 0; m < 4; ++m)
; #pragma unroll
;                 for (int n = 0; n < 2; ++n) acc[a][b][m][n] = (f32x4){0.f, 0.f, 0.f, 0.f};
;     bf16x8 At[4][2], B0[2][2], B1[2][2];
;     const char* cA = (const char*)g.A + (size_t)cur.pm * tA + (size_t)cur.k0 * 2; const char* cB = (const char*)g.Bt + (size_t)cur.pn * tB + (size_t)cur.k0 * 2;
;     PG8_STAGE(PG8_SB(0, 0), cB, voffB); PG8_STAGE(PG8_SB(0, 1), cB + hB, voffB); PG8_STAGE(PG8_SA(0, 0), cA, voffA); PG8_STAGE(PG8_SA(0, 1), cA + hA, voffA);
;     if (wr == 1) PG8_BAR;
;     PG8_WAIT_V(2); PG8_BAR;
;     PG8_STAGE(PG8_SB(1, 0), cB + kstep, voffB); PG8_STAGE(PG8_SA(1, 0), cA + kstepA, voffA); PG8_STAGE(PG8_SB(1, 1), cB + hB + kstep, voffB);
;     PG8_WAIT_V(6); PG8_BAR;
;     for (;;) {
;         const bool has_next = S.next(ui + 1, nxt);
;         const char* nA = has_next ? (const char*)g.A + (size_t)nxt.pm * tA + (size_t)nxt.k0 * 2 : cA; const char* nB = has_next ? (const char*)g.Bt + (size_t)nxt.pn * tB + (size_t)nxt.k0 * 2 : cB;
.LBB0_258:
	s_ashr_i32 s17, s16, 31
	s_lshl_b64 s[18:19], s[16:17], 20
	v_readlane_b32 s20, v253, 34
	v_readlane_b32 s21, v253, 35
	s_add_u32 s18, s20, s18
	s_addc_u32 s19, s21, s19
	s_and_b64 s[20:21], s[0:1], exec
	s_cselect_b32 s17, s19, s3
	s_cselect_b32 s26, s18, s2
	s_ashr_i32 s15, s14, 31
	s_lshl_b64 s[20:21], s[14:15], 20
	s_add_u32 s20, s30, s20
	s_addc_u32 s21, s31, s21
	s_and_b64 s[24:25], s[0:1], exec
	s_cselect_b32 s15, s21, s23
	s_cselect_b32 s27, s20, s22
	s_add_u32 s2, s2, 0x80080
	s_addc_u32 s3, s3, 0
	s_add_u32 s28, s22, 0x100
	s_waitcnt vmcnt(12)
	v_mov_b64_e32 v[2:3], v[206:207]
	v_mov_b64_e32 v[4:5], v[208:209]
	v_mov_b64_e32 v[6:7], v[202:203]
	v_mov_b64_e32 v[8:9], v[204:205]
	v_mov_b64_e32 v[10:11], v[198:199]
	v_mov_b64_e32 v[12:13], v[200:201]
	v_mov_b64_e32 v[14:15], v[194:195]
	v_mov_b64_e32 v[16:17], v[196:197]
	v_mov_b64_e32 v[18:19], v[206:207]
	v_mov_b64_e32 v[20:21], v[208:209]
	v_mov_b64_e32 v[22:23], v[202:203]
	v_mov_b64_e32 v[24:25], v[204:205]
	v_mov_b64_e32 v[26:27], v[198:199]
	v_mov_b64_e32 v[28:29], v[200:201]
	v_mov_b64_e32 v[30:31], v[194:195]
	v_mov_b64_e32 v[32:33], v[196:197]
	v_mov_b64_e32 v[34:35], v[206:207]
	v_mov_b64_e32 v[36:37], v[208:209]
	v_mov_b64_e32 v[38:39], v[202:203]
	v_mov_b64_e32 v[40:41], v[204:205]
	v_mov_b64_e32 v[50:51], v[198:199]
	v_mov_b64_e32 v[52:53], v[200:201]
	v_mov_b64_e32 v[54:55], v[194:195]
	v_mov_b64_e32 v[56:57], v[196:197]
	v_mov_b64_e32 v[66:67], v[206:207]
	v_mov_b64_e32 v[68:69], v[208:209]
	v_mov_b64_e32 v[70:71], v[202:203]
	v_mov_b64_e32 v[72:73], v[204:205]
	v_mov_b64_e32 v[74:75], v[198:199]
	v_mov_b64_e32 v[76:77], v[200:201]
	v_mov_b64_e32 v[78:79], v[194:195]
	v_mov_b64_e32 v[80:81], v[196:197]
	v_mov_b64_e32 v[82:83], v[206:207]
	v_mov_b64_e32 v[84:85], v[208:209]
	v_mov_b64_e32 v[86:87], v[202:203]
	v_mov_b64_e32 v[88:89], v[204:205]
	v_mov_b64_e32 v[90:91], v[198:199]
	v_mov_b64_e32 v[92:93], v[200:201]
	v_mov_b64_e32 v[94:95], v[194:195]
	v_mov_b64_e32 v[96:97], v[196:197]
	v_mov_b64_e32 v[100:101], v[206:207]
	v_mov_b64_e32 v[102:103], v[208:209]
	v_mov_b64_e32 v[104:105], v[202:203]
	v_mov_b64_e32 v[106:107], v[204:205]
	v_mov_b64_e32 v[108:109], v[198:199]
	v_mov_b64_e32 v[110:111], v[200:201]
	v_mov_b64_e32 v[112:113], v[194:195]
	v_mov_b64_e32 v[114:115], v[196:197]
	v_mov_b64_e32 v[116:117], v[206:207]
	v_mov_b64_e32 v[118:119], v[208:209]
	v_mov_b64_e32 v[120:121], v[202:203]
	v_mov_b64_e32 v[122:123], v[204:205]
	v_mov_b64_e32 v[124:125], v[198:199]
	v_mov_b64_e32 v[126:127], v[200:201]
	v_mov_b64_e32 v[128:129], v[194:195]
	v_mov_b64_e32 v[130:131], v[196:197]
	v_mov_b64_e32 v[132:133], v[206:207]
	v_mov_b64_e32 v[134:135], v[208:209]
	v_mov_b64_e32 v[136:137], v[202:203]
	v_mov_b64_e32 v[138:139], v[204:205]
	v_mov_b64_e32 v[140:141], v[198:199]
	v_mov_b64_e32 v[142:143], v[200:201]
	v_mov_b64_e32 v[144:145], v[194:195]
	v_mov_b64_e32 v[146:147], v[196:197]
	s_addc_u32 s29, s23, 0
	s_mov_b32 s46, -2

; __device__ __forceinline__ float fast_sigmoid(float v) { return __builtin_amdgcn_rcpf(1.0f + __builtin_amdgcn_exp2f(-v * LOG2E)); }
; __device__ __forceinline__ u32x4 pack8(f32x4 a, f32x4 b) { u32x4 w; w.x = cvt_pk_bf16(a[0], a[1]); w.y = cvt_pk_bf16(a[2], a[3]); w.z = cvt_pk_bf16(b[0], b[1]); w.w = cvt_pk_bf16(b[2], b[3]); return w; }
;     __device__ __forceinline__ void operator()(Acc& acc, const Unit& u, int wr, int wc, int fr, int fq) const {
;         const int rowb = u.pm * BM + wr * 64 + fr, colb = u.pn * BM + wc * 64 + 8 * fq;
;         bf16* base; int sA, sM2, sM1; bool sig = false;
;         if (u.pn < 12) { base = qkv + (size_t)rowb * 3072 + colb; sA = 128 * 3072; sM2 = 32 * 3072; sM1 = 16 * 3072; }
;         else if (u.pn < 14) { const int ch = colb - 3072, gg = ch >> 4, c = ch & 15;
;             base = a2 + ((size_t)(gg * ROWS_G + u.pm * 8 + wr * 2) * K2 + fr * 16 + c); sA = 4 * K2; sM2 = K2; sM1 = 256; }
;         else if (u.pn < 16) { base = qm + (size_t)rowb * 512 + (colb - 3584); sA = 128 * 512; sM2 = 32 * 512; sM1 = 16 * 512; }
;         else { base = (bf16*)(gates + (size_t)rowb * 6144 + (colb - 4096)); sA = 64 * 6144; sM2 = 16 * 6144; sM1 = 8 * 6144; sig = true; }
;         const int sB = (u.pn >= 12 && u.pn < 14) ? 2 * ROWS_G * K2 : (u.pn >= 16 ? BJ / 2 : BJ);
;         f32x4 bv[2][2];
; #pragma unroll
;         for (int bj = 0; bj < 2; ++bj)
; #pragma unroll
;             for (int n = 0; n < 2; ++n) bv[bj][n] = *(const f32x4*)(bias + colb + bj * BJ + 4 * n);
; #pragma unroll
;         for (int ai = 0; ai < 2; ++ai)
; #pragma unroll
;             for (int m = 0; m < 4; ++m) { bf16* rowp = base + (size_t)ai * sA + (size_t)(m >> 1) * sM2 + (size_t)(m & 1) * sM1;
; #pragma unroll
;                 for (int bj = 0; bj < 2; ++bj) { f32x4 v0 = acc[ai][bj][m][0] + bv[bj][0], v1 = acc[ai][bj][m][1] + bv[bj][1];
;                     if (sig) {
; #pragma unroll
;                         for (int e = 0; e < 4; ++e) { v0[e] = fast_sigmoid(v0[e]); v1[e] = fast_sigmoid(v1[e]); }
;                         *(u32x2*)(rowp + (size_t)bj * sB) = (u32x2){pack_gate4(v0), pack_gate4(v1)}; }
;                     else *(u32x4*)(rowp + (size_t)bj * sB) = pack8(v0, v1); } }
.LBB0_273:
	v_mov_b32_e32 v42, v98
	v_lshl_add_u64 v[46:47], v[42:43], 2, s[8:9]
	s_and_b64 vcc, exec, s[0:1]
	s_cbranch_vccz .Lip_nopref
	v_lshl_or_b32 v210, s14, 8, v176
	v_mov_b32_e32 v211, 0
	v_lshl_add_u64 v[210:211], v[210:211], 2, s[8:9]
	global_load_dwordx4 v[194:197], v[210:211], off
	global_load_dwordx4 v[198:201], v[210:211], off offset:16
	global_load_dwordx4 v[202:205], v[210:211], off offset:128
	global_load_dwordx4 v[206:209], v[210:211], off offset:144
.Lip_nopref:
	s_xor_b64 s[26:27], s[26:27], -1
	s_mov_b64 s[28:29], -1
	s_and_b64 vcc, exec, s[26:27]
	s_mov_b32 s57, 0xfffe
	s_cbranch_vccz .LBB0_275
	v_cvt_pk_bf16_f32 v178, v144, v145
	v_cvt_pk_bf16_f32 v179, v146, v147
	v_cvt_pk_bf16_f32 v180, v140, v141
	v_cvt_pk_bf16_f32 v181, v142, v143
	global_store_dwordx4 v[172:173], v[178:181], off
	s_mov_b64 s[28:29], 0

; __device__ __forceinline__ float fast_sigmoid(float v) { return __builtin_amdgcn_rcpf(1.0f + __builtin_amdgcn_exp2f(-v * LOG2E)); }
; __device__ __forceinline__ u32x4 pack8(f32x4 a, f32x4 b) { u32x4 w; w.x = cvt_pk_bf16(a[0], a[1]); w.y = cvt_pk_bf16(a[2], a[3]); w.z = cvt_pk_bf16(b[0], b[1]); w.w = cvt_pk_bf16(b[2], b[3]); return w; }
;     __device__ __forceinline__ void operator()(Acc& acc, const Unit& u, int wr, int wc, int fr, int fq) const {
;     ...
;         const int sB = (u.pn >= 12 && u.pn < 14) ? 2 * ROWS_G * K2 : (u.pn >= 16 ? BJ / 2 : BJ);
;         f32x4 bv[2][2];
; #pragma unroll
;         for (int bj = 0; bj < 2; ++bj)
; #pragma unroll
;             for (int n = 0; n < 2; ++n) bv[bj][n] = *(const f32x4*)(bias + colb + bj * BJ + 4 * n);
; #pragma unroll
;         for (int ai = 0; ai < 2; ++ai)
; #pragma unroll
;             for (int m = 0; m < 4; ++m) { bf16* rowp = base + (size_t)ai * sA + (size_t)(m >> 1) * sM2 + (size_t)(m & 1) * sM1;
; #pragma unroll
;                 for (int bj = 0; bj < 2; ++bj) { f32x4 v0 = acc[ai][bj][m][0] + bv[bj][0], v1 = acc[ai][bj][m][1] + bv[bj][1];
;                     if (sig) {
; #pragma unroll
;                         for (int e = 0; e < 4; ++e) { v0[e] = fast_sigmoid(v0[e]); v1[e] = fast_sigmoid(v1[e]); }
;                         *(u32x2*)(rowp + (size_t)bj * sB) = (u32x2){pack_gate4(v0), pack_gate4(v1)}; }
;                     else *(u32x4*)(rowp + (size_t)bj * sB) = pack8(v0, v1); } }
.LBB0_277:
	s_and_b32 s15, s10, -2
	s_cmp_lt_i32 s10, 16
	s_cselect_b32 s10, 32, 16
	s_cmp_lg_u32 s15, 12
	v_cndmask_b32_e64 v98, 0, 1, s[26:27]
	s_cselect_b32 s15, s10, 0x140000
	v_cmp_ne_u32_e64 s[70:71], 1, v98
	s_andn2_b64 vcc, exec, s[26:27]
	s_mov_b64 s[26:27], -1
	s_cbranch_vccnz .LBB0_279
	v_readlane_b32 s26, v254, 3
	v_readlane_b32 s27, v254, 4
	s_mov_b32 s17, s27
	s_lshl_b32 s26, s15, 1
	v_writelane_b32 v254, s16, 3
	v_cvt_pk_bf16_f32 v140, v136, v137
	v_cvt_pk_bf16_f32 v141, v138, v139
	v_cvt_pk_bf16_f32 v142, v132, v133
	v_cvt_pk_bf16_f32 v143, v134, v135
	v_writelane_b32 v254, s17, 4
	v_lshl_add_u64 v[144:145], v[172:173], 0, s[26:27]
	s_mov_b64 s[26:27], 0
	global_store_dwordx4 v[144:145], v[140:143], off

; __device__ __forceinline__ float fast_sigmoid(float v) { return __builtin_amdgcn_rcpf(1.0f + __builtin_amdgcn_exp2f(-v * LOG2E)); }
; __device__ __forceinline__ u32x4 pack8(f32x4 a, f32x4 b) { u32x4 w; w.x = cvt_pk_bf16(a[0], a[1]); w.y = cvt_pk_bf16(a[2], a[3]); w.z = cvt_pk_bf16(b[0], b[1]); w.w = cvt_pk_bf16(b[2], b[3]); return w; }
;     __device__ __forceinline__ void operator()(Acc& acc, const Unit& u, int wr, int wc, int fr, int fq) const {
;     ...
;         for (int ai = 0; ai < 2; ++ai)
; #pragma unroll
;             for (int m = 0; m < 4; ++m) { bf16* rowp = base + (size_t)ai * sA + (size_t)(m >> 1) * sM2 + (size_t)(m & 1) * sM1;
; #pragma unroll
;                 for (int bj = 0; bj < 2; ++bj) { f32x4 v0 = acc[ai][bj][m][0] + bv[bj][0], v1 = acc[ai][bj][m][1] + bv[bj][1];
;                     if (sig) {
; #pragma unroll
;                         for (int e = 0; e < 4; ++e) { v0[e] = fast_sigmoid(v0[e]); v1[e] = fast_sigmoid(v1[e]); }
;                         *(u32x2*)(rowp + (size_t)bj * sB) = (u32x2){pack_gate4(v0), pack_gate4(v1)}; }
;                     else *(u32x4*)(rowp + (size_t)bj * sB) = pack8(v0, v1); } }
.LBB0_281:
	v_lshl_add_u64 v[132:133], s[2:3], 1, v[172:173]
	s_and_b64 vcc, exec, s[70:71]
	s_mov_b64 s[26:27], -1
	s_cbranch_vccnz .LBB0_283
	v_cvt_pk_bf16_f32 v134, v128, v129
	v_cvt_pk_bf16_f32 v135, v130, v131
	v_cvt_pk_bf16_f32 v136, v124, v125
	v_cvt_pk_bf16_f32 v137, v126, v127
	s_mov_b64 s[26:27], 0
	global_store_dwordx4 v[132:133], v[134:137], off

; __device__ __forceinline__ float fast_sigmoid(float v) { return __builtin_amdgcn_rcpf(1.0f + __builtin_amdgcn_exp2f(-v * LOG2E)); }
; __device__ __forceinline__ u32x4 pack8(f32x4 a, f32x4 b) { u32x4 w; w.x = cvt_pk_bf16(a[0], a[1]); w.y = cvt_pk_bf16(a[2], a[3]); w.z = cvt_pk_bf16(b[0], b[1]); w.w = cvt_pk_bf16(b[2], b[3]); return w; }
;     __device__ __forceinline__ void operator()(Acc& acc, const Unit& u, int wr, int wc, int fr, int fq) const {
;     ...
;         for (int ai = 0; ai < 2; ++ai)
; #pragma unroll
;             for (int m = 0; m < 4; ++m) { bf16* rowp = base + (size_t)ai * sA + (size_t)(m >> 1) * sM2 + (size_t)(m & 1) * sM1;
; #pragma unroll
;                 for (int bj = 0; bj < 2; ++bj) { f32x4 v0 = acc[ai][bj][m][0] + bv[bj][0], v1 = acc[ai][bj][m][1] + bv[bj][1];
;                     if (sig) {
; #pragma unroll
;                         for (int e = 0; e < 4; ++e) { v0[e] = fast_sigmoid(v0[e]); v1[e] = fast_sigmoid(v1[e]); }
;                         *(u32x2*)(rowp + (size_t)bj * sB) = (u32x2){pack_gate4(v0), pack_gate4(v1)}; }
;                     else *(u32x4*)(rowp + (size_t)bj * sB) = pack8(v0, v1); } }
.LBB0_285:
	s_and_b64 vcc, exec, s[70:71]
	s_mov_b64 s[26:27], -1
	s_cbranch_vccnz .LBB0_287
	v_readlane_b32 s26, v254, 3
	v_readlane_b32 s27, v254, 4
	s_mov_b32 s17, s27
	s_lshl_b32 s26, s15, 1
	v_writelane_b32 v254, s16, 3
	v_cvt_pk_bf16_f32 v124, v120, v121
	v_cvt_pk_bf16_f32 v125, v122, v123
	v_cvt_pk_bf16_f32 v126, v116, v117
	v_cvt_pk_bf16_f32 v127, v118, v119
	v_writelane_b32 v254, s17, 4
	v_lshl_add_u64 v[128:129], v[132:133], 0, s[26:27]
	s_mov_b64 s[26:27], 0
	global_store_dwordx4 v[128:129], v[124:127], off

; __device__ __forceinline__ float fast_sigmoid(float v) { return __builtin_amdgcn_rcpf(1.0f + __builtin_amdgcn_exp2f(-v * LOG2E)); }
; __device__ __forceinline__ u32x4 pack8(f32x4 a, f32x4 b) { u32x4 w; w.x = cvt_pk_bf16(a[0], a[1]); w.y = cvt_pk_bf16(a[2], a[3]); w.z = cvt_pk_bf16(b[0], b[1]); w.w = cvt_pk_bf16(b[2], b[3]); return w; }
;     __device__ __forceinline__ void operator()(Acc& acc, const Unit& u, int wr, int wc, int fr, int fq) const {
;     ...
;         for (int ai = 0; ai < 2; ++ai)
; #pragma unroll
;             for (int m = 0; m < 4; ++m) { bf16* rowp = base + (size_t)ai * sA + (size_t)(m >> 1) * sM2 + (size_t)(m & 1) * sM1;
; #pragma unroll
;                 for (int bj = 0; bj < 2; ++bj) { f32x4 v0 = acc[ai][bj][m][0] + bv[bj][0], v1 = acc[ai][bj][m][1] + bv[bj][1];
;                     if (sig) {
; #pragma unroll
;                         for (int e = 0; e < 4; ++e) { v0[e] = fast_sigmoid(v0[e]); v1[e] = fast_sigmoid(v1[e]); }
;                         *(u32x2*)(rowp + (size_t)bj * sB) = (u32x2){pack_gate4(v0), pack_gate4(v1)}; }
;                     else *(u32x4*)(rowp + (size_t)bj * sB) = pack8(v0, v1); } }
.LBB0_289:
	v_lshl_add_u64 v[116:117], s[22:23], 1, v[172:173]
	s_and_b64 vcc, exec, s[70:71]
	s_mov_b64 s[26:27], -1
	s_cbranch_vccnz .LBB0_291
	v_cvt_pk_bf16_f32 v118, v112, v113
	v_cvt_pk_bf16_f32 v119, v114, v115
	v_cvt_pk_bf16_f32 v120, v108, v109
	v_cvt_pk_bf16_f32 v121, v110, v111
	s_mov_b64 s[26:27], 0
	global_store_dwordx4 v[116:117], v[118:121], off

; __device__ __forceinline__ float fast_sigmoid(float v) { return __builtin_amdgcn_rcpf(1.0f + __builtin_amdgcn_exp2f(-v * LOG2E)); }
; __device__ __forceinline__ u32x4 pack8(f32x4 a, f32x4 b) { u32x4 w; w.x = cvt_pk_bf16(a[0], a[1]); w.y = cvt_pk_bf16(a[2], a[3]); w.z = cvt_pk_bf16(b[0], b[1]); w.w = cvt_pk_bf16(b[2], b[3]); return w; }
;     __device__ __forceinline__ void operator()(Acc& acc, const Unit& u, int wr, int wc, int fr, int fq) const {
;     ...
;         for (int ai = 0; ai < 2; ++ai)
; #pragma unroll
;             for (int m = 0; m < 4; ++m) { bf16* rowp = base + (size_t)ai * sA + (size_t)(m >> 1) * sM2 + (size_t)(m & 1) * sM1;
; #pragma unroll
;                 for (int bj = 0; bj < 2; ++bj) { f32x4 v0 = acc[ai][bj][m][0] + bv[bj][0], v1 = acc[ai][bj][m][1] + bv[bj][1];
;                     if (sig) {
; #pragma unroll
;                         for (int e = 0; e < 4; ++e) { v0[e] = fast_sigmoid(v0[e]); v1[e] = fast_sigmoid(v1[e]); }
;                         *(u32x2*)(rowp + (size_t)bj * sB) = (u32x2){pack_gate4(v0), pack_gate4(v1)}; }
;                     else *(u32x4*)(rowp + (size_t)bj * sB) = pack8(v0, v1); } }
.LBB0_293:
	s_and_b64 vcc, exec, s[70:71]
	s_mov_b64 s[26:27], -1
	s_cbranch_vccnz .LBB0_295
	v_readlane_b32 s26, v254, 3
	v_readlane_b32 s27, v254, 4
	s_mov_b32 s17, s27
	s_lshl_b32 s26, s15, 1
	v_writelane_b32 v254, s16, 3
	v_cvt_pk_bf16_f32 v108, v104, v105
	v_cvt_pk_bf16_f32 v109, v106, v107
	v_cvt_pk_bf16_f32 v110, v100, v101
	v_cvt_pk_bf16_f32 v111, v102, v103
	v_writelane_b32 v254, s17, 4
	v_lshl_add_u64 v[112:113], v[116:117], 0, s[26:27]
	s_mov_b64 s[26:27], 0
	global_store_dwordx4 v[112:113], v[108:111], off

; __device__ __forceinline__ float fast_sigmoid(float v) { return __builtin_amdgcn_rcpf(1.0f + __builtin_amdgcn_exp2f(-v * LOG2E)); }
; __device__ __forceinline__ u32x4 pack8(f32x4 a, f32x4 b) { u32x4 w; w.x = cvt_pk_bf16(a[0], a[1]); w.y = cvt_pk_bf16(a[2], a[3]); w.z = cvt_pk_bf16(b[0], b[1]); w.w = cvt_pk_bf16(b[2], b[3]); return w; }
;     __device__ __forceinline__ void operator()(Acc& acc, const Unit& u, int wr, int wc, int fr, int fq) const {
;     ...
;         for (int ai = 0; ai < 2; ++ai)
; #pragma unroll
;             for (int m = 0; m < 4; ++m) { bf16* rowp = base + (size_t)ai * sA + (size_t)(m >> 1) * sM2 + (size_t)(m & 1) * sM1;
; #pragma unroll
;                 for (int bj = 0; bj < 2; ++bj) { f32x4 v0 = acc[ai][bj][m][0] + bv[bj][0], v1 = acc[ai][bj][m][1] + bv[bj][1];
;                     if (sig) {
; #pragma unroll
;                         for (int e = 0; e < 4; ++e) { v0[e] = fast_sigmoid(v0[e]); v1[e] = fast_sigmoid(v1[e]); }
;                         *(u32x2*)(rowp + (size_t)bj * sB) = (u32x2){pack_gate4(v0), pack_gate4(v1)}; }
;                     else *(u32x4*)(rowp + (size_t)bj * sB) = pack8(v0, v1); } }
.LBB0_297:
	v_lshl_add_u64 v[100:101], s[2:3], 1, v[116:117]
	s_and_b64 vcc, exec, s[70:71]
	s_mov_b64 s[26:27], -1
	s_cbranch_vccnz .LBB0_299
	v_cvt_pk_bf16_f32 v102, v94, v95
	v_cvt_pk_bf16_f32 v103, v96, v97
	v_cvt_pk_bf16_f32 v104, v90, v91
	v_cvt_pk_bf16_f32 v105, v92, v93
	s_mov_b64 s[26:27], 0
	global_store_dwordx4 v[100:101], v[102:105], off

; __device__ __forceinline__ float fast_sigmoid(float v) { return __builtin_amdgcn_rcpf(1.0f + __builtin_amdgcn_exp2f(-v * LOG2E)); }
; __device__ __forceinline__ u32x4 pack8(f32x4 a, f32x4 b) { u32x4 w; w.x = cvt_pk_bf16(a[0], a[1]); w.y = cvt_pk_bf16(a[2], a[3]); w.z = cvt_pk_bf16(b[0], b[1]); w.w = cvt_pk_bf16(b[2], b[3]); return w; }
;     __device__ __forceinline__ void operator()(Acc& acc, const Unit& u, int wr, int wc, int fr, int fq) const {
;     ...
;         for (int ai = 0; ai < 2; ++ai)
; #pragma unroll
;             for (int m = 0; m < 4; ++m) { bf16* rowp = base + (size_t)ai * sA + (size_t)(m >> 1) * sM2 + (size_t)(m & 1) * sM1;
; #pragma unroll
;                 for (int bj = 0; bj < 2; ++bj) { f32x4 v0 = acc[ai][bj][m][0] + bv[bj][0], v1 = acc[ai][bj][m][1] + bv[bj][1];
;                     if (sig) {
; #pragma unroll
;                         for (int e = 0; e < 4; ++e) { v0[e] = fast_sigmoid(v0[e]); v1[e] = fast_sigmoid(v1[e]); }
;                         *(u32x2*)(rowp + (size_t)bj * sB) = (u32x2){pack_gate4(v0), pack_gate4(v1)}; }
;                     else *(u32x4*)(rowp + (size_t)bj * sB) = pack8(v0, v1); } }
.LBB0_301:
	s_and_b64 vcc, exec, s[70:71]
	s_mov_b64 s[26:27], -1
	s_cbranch_vccnz .LBB0_303
	v_readlane_b32 s26, v254, 3
	v_readlane_b32 s27, v254, 4
	s_mov_b32 s17, s27
	s_lshl_b32 s26, s15, 1
	v_writelane_b32 v254, s16, 3
	v_cvt_pk_bf16_f32 v90, v86, v87
	v_cvt_pk_bf16_f32 v91, v88, v89
	v_cvt_pk_bf16_f32 v92, v82, v83
	v_cvt_pk_bf16_f32 v93, v84, v85
	v_writelane_b32 v254, s17, 4
	v_lshl_add_u64 v[94:95], v[100:101], 0, s[26:27]
	s_mov_b64 s[26:27], 0
	global_store_dwordx4 v[94:95], v[90:93], off

; __device__ __forceinline__ float fast_sigmoid(float v) { return __builtin_amdgcn_rcpf(1.0f + __builtin_amdgcn_exp2f(-v * LOG2E)); }
; __device__ __forceinline__ u32x4 pack8(f32x4 a, f32x4 b) { u32x4 w; w.x = cvt_pk_bf16(a[0], a[1]); w.y = cvt_pk_bf16(a[2], a[3]); w.z = cvt_pk_bf16(b[0], b[1]); w.w = cvt_pk_bf16(b[2], b[3]); return w; }
;     __device__ __forceinline__ void operator()(Acc& acc, const Unit& u, int wr, int wc, int fr, int fq) const {
;     ...
;         for (int ai = 0; ai < 2; ++ai)
; #pragma unroll
;             for (int m = 0; m < 4; ++m) { bf16* rowp = base + (size_t)ai * sA + (size_t)(m >> 1) * sM2 + (size_t)(m & 1) * sM1;
; #pragma unroll
;                 for (int bj = 0; bj < 2; ++bj) { f32x4 v0 = acc[ai][bj][m][0] + bv[bj][0], v1 = acc[ai][bj][m][1] + bv[bj][1];
;                     if (sig) {
; #pragma unroll
;                         for (int e = 0; e < 4; ++e) { v0[e] = fast_sigmoid(v0[e]); v1[e] = fast_sigmoid(v1[e]); }
;                         *(u32x2*)(rowp + (size_t)bj * sB) = (u32x2){pack_gate4(v0), pack_gate4(v1)}; }
;                     else *(u32x4*)(rowp + (size_t)bj * sB) = pack8(v0, v1); } }
.LBB0_305:
	v_lshl_add_u64 v[82:83], s[24:25], 1, v[172:173]
	s_and_b64 vcc, exec, s[70:71]
	s_mov_b64 s[24:25], -1
	s_cbranch_vccnz .LBB0_307
	v_cvt_pk_bf16_f32 v84, v78, v79
	v_cvt_pk_bf16_f32 v85, v80, v81
	v_cvt_pk_bf16_f32 v86, v74, v75
	v_cvt_pk_bf16_f32 v87, v76, v77
	s_mov_b64 s[24:25], 0
	global_store_dwordx4 v[82:83], v[84:87], off

; __device__ __forceinline__ float fast_sigmoid(float v) { return __builtin_amdgcn_rcpf(1.0f + __builtin_amdgcn_exp2f(-v * LOG2E)); }
; __device__ __forceinline__ u32x4 pack8(f32x4 a, f32x4 b) { u32x4 w; w.x = cvt_pk_bf16(a[0], a[1]); w.y = cvt_pk_bf16(a[2], a[3]); w.z = cvt_pk_bf16(b[0], b[1]); w.w = cvt_pk_bf16(b[2], b[3]); return w; }
;     __device__ __forceinline__ void operator()(Acc& acc, const Unit& u, int wr, int wc, int fr, int fq) const {
;     ...
;         for (int ai = 0; ai < 2; ++ai)
; #pragma unroll
;             for (int m = 0; m < 4; ++m) { bf16* rowp = base + (size_t)ai * sA + (size_t)(m >> 1) * sM2 + (size_t)(m & 1) * sM1;
; #pragma unroll
;                 for (int bj = 0; bj < 2; ++bj) { f32x4 v0 = acc[ai][bj][m][0] + bv[bj][0], v1 = acc[ai][bj][m][1] + bv[bj][1];
;                     if (sig) {
; #pragma unroll
;                         for (int e = 0; e < 4; ++e) { v0[e] = fast_sigmoid(v0[e]); v1[e] = fast_sigmoid(v1[e]); }
;                         *(u32x2*)(rowp + (size_t)bj * sB) = (u32x2){pack_gate4(v0), pack_gate4(v1)}; }
;                     else *(u32x4*)(rowp + (size_t)bj * sB) = pack8(v0, v1); } }
.LBB0_309:
	s_and_b64 vcc, exec, s[70:71]
	s_mov_b64 s[24:25], -1
	s_cbranch_vccnz .LBB0_311
	v_readlane_b32 s24, v254, 3
	v_readlane_b32 s25, v254, 4
	s_mov_b32 s17, s25
	s_lshl_b32 s24, s15, 1
	v_writelane_b32 v254, s16, 3
	v_cvt_pk_bf16_f32 v74, v70, v71
	v_cvt_pk_bf16_f32 v75, v72, v73
	v_cvt_pk_bf16_f32 v76, v66, v67
	v_cvt_pk_bf16_f32 v77, v68, v69
	v_writelane_b32 v254, s17, 4
	v_lshl_add_u64 v[78:79], v[82:83], 0, s[24:25]
	s_mov_b64 s[24:25], 0
	global_store_dwordx4 v[78:79], v[74:77], off

; __device__ __forceinline__ float fast_sigmoid(float v) { return __builtin_amdgcn_rcpf(1.0f + __builtin_amdgcn_exp2f(-v * LOG2E)); }
; __device__ __forceinline__ u32x4 pack8(f32x4 a, f32x4 b) { u32x4 w; w.x = cvt_pk_bf16(a[0], a[1]); w.y = cvt_pk_bf16(a[2], a[3]); w.z = cvt_pk_bf16(b[0], b[1]); w.w = cvt_pk_bf16(b[2], b[3]); return w; }
;     __device__ __forceinline__ void operator()(Acc& acc, const Unit& u, int wr, int wc, int fr, int fq) const {
;     ...
;         for (int ai = 0; ai < 2; ++ai)
; #pragma unroll
;             for (int m = 0; m < 4; ++m) { bf16* rowp = base + (size_t)ai * sA + (size_t)(m >> 1) * sM2 + (size_t)(m & 1) * sM1;
; #pragma unroll
;                 for (int bj = 0; bj < 2; ++bj) { f32x4 v0 = acc[ai][bj][m][0] + bv[bj][0], v1 = acc[ai][bj][m][1] + bv[bj][1];
;                     if (sig) {
; #pragma unroll
;                         for (int e = 0; e < 4; ++e) { v0[e] = fast_sigmoid(v0[e]); v1[e] = fast_sigmoid(v1[e]); }
;                         *(u32x2*)(rowp + (size_t)bj * sB) = (u32x2){pack_gate4(v0), pack_gate4(v1)}; }
;                     else *(u32x4*)(rowp + (size_t)bj * sB) = pack8(v0, v1); } }
.LBB0_313:
	v_lshl_add_u64 v[66:67], s[2:3], 1, v[82:83]
	s_and_b64 vcc, exec, s[70:71]
	s_mov_b64 s[24:25], -1
	s_cbranch_vccnz .LBB0_315
	v_cvt_pk_bf16_f32 v68, v54, v55
	v_cvt_pk_bf16_f32 v69, v56, v57
	v_cvt_pk_bf16_f32 v70, v50, v51
	v_cvt_pk_bf16_f32 v71, v52, v53
	s_mov_b64 s[24:25], 0
	global_store_dwordx4 v[66:67], v[68:71], off

; __device__ __forceinline__ float fast_sigmoid(float v) { return __builtin_amdgcn_rcpf(1.0f + __builtin_amdgcn_exp2f(-v * LOG2E)); }
; __device__ __forceinline__ u32x4 pack8(f32x4 a, f32x4 b) { u32x4 w; w.x = cvt_pk_bf16(a[0], a[1]); w.y = cvt_pk_bf16(a[2], a[3]); w.z = cvt_pk_bf16(b[0], b[1]); w.w = cvt_pk_bf16(b[2], b[3]); return w; }
;     __device__ __forceinline__ void operator()(Acc& acc, const Unit& u, int wr, int wc, int fr, int fq) const {
;     ...
;         for (int ai = 0; ai < 2; ++ai)
; #pragma unroll
;             for (int m = 0; m < 4; ++m) { bf16* rowp = base + (size_t)ai * sA + (size_t)(m >> 1) * sM2 + (size_t)(m & 1) * sM1;
; #pragma unroll
;                 for (int bj = 0; bj < 2; ++bj) { f32x4 v0 = acc[ai][bj][m][0] + bv[bj][0], v1 = acc[ai][bj][m][1] + bv[bj][1];
;                     if (sig) {
; #pragma unroll
;                         for (int e = 0; e < 4; ++e) { v0[e] = fast_sigmoid(v0[e]); v1[e] = fast_sigmoid(v1[e]); }
;                         *(u32x2*)(rowp + (size_t)bj * sB) = (u32x2){pack_gate4(v0), pack_gate4(v1)}; }
;                     else *(u32x4*)(rowp + (size_t)bj * sB) = pack8(v0, v1); } }
.LBB0_317:
	s_and_b64 vcc, exec, s[70:71]
	s_mov_b64 s[24:25], -1
	s_cbranch_vccnz .LBB0_319
	v_readlane_b32 s24, v254, 3
	v_readlane_b32 s25, v254, 4
	s_mov_b32 s17, s25
	s_lshl_b32 s24, s15, 1
	v_writelane_b32 v254, s16, 3
	v_cvt_pk_bf16_f32 v50, v38, v39
	v_cvt_pk_bf16_f32 v51, v40, v41
	v_cvt_pk_bf16_f32 v52, v34, v35
	v_cvt_pk_bf16_f32 v53, v36, v37
	v_writelane_b32 v254, s17, 4
	v_lshl_add_u64 v[54:55], v[66:67], 0, s[24:25]
	s_mov_b64 s[24:25], 0
	global_store_dwordx4 v[54:55], v[50:53], off

; __device__ __forceinline__ float fast_sigmoid(float v) { return __builtin_amdgcn_rcpf(1.0f + __builtin_amdgcn_exp2f(-v * LOG2E)); }
; __device__ __forceinline__ u32x4 pack8(f32x4 a, f32x4 b) { u32x4 w; w.x = cvt_pk_bf16(a[0], a[1]); w.y = cvt_pk_bf16(a[2], a[3]); w.z = cvt_pk_bf16(b[0], b[1]); w.w = cvt_pk_bf16(b[2], b[3]); return w; }
;     __device__ __forceinline__ void operator()(Acc& acc, const Unit& u, int wr, int wc, int fr, int fq) const {
;     ...
;         for (int ai = 0; ai < 2; ++ai)
; #pragma unroll
;             for (int m = 0; m < 4; ++m) { bf16* rowp = base + (size_t)ai * sA + (size_t)(m >> 1) * sM2 + (size_t)(m & 1) * sM1;
; #pragma unroll
;                 for (int bj = 0; bj < 2; ++bj) { f32x4 v0 = acc[ai][bj][m][0] + bv[bj][0], v1 = acc[ai][bj][m][1] + bv[bj][1];
;                     if (sig) {
; #pragma unroll
;                         for (int e = 0; e < 4; ++e) { v0[e] = fast_sigmoid(v0[e]); v1[e] = fast_sigmoid(v1[e]); }
;                         *(u32x2*)(rowp + (size_t)bj * sB) = (u32x2){pack_gate4(v0), pack_gate4(v1)}; }
;                     else *(u32x4*)(rowp + (size_t)bj * sB) = pack8(v0, v1); } }
.LBB0_321:
	v_lshl_add_u64 v[34:35], s[22:23], 1, v[82:83]
	s_and_b64 vcc, exec, s[70:71]
	s_mov_b64 s[22:23], -1
	s_cbranch_vccnz .LBB0_323
	v_cvt_pk_bf16_f32 v36, v30, v31
	v_cvt_pk_bf16_f32 v37, v32, v33
	v_cvt_pk_bf16_f32 v38, v26, v27
	v_cvt_pk_bf16_f32 v39, v28, v29
	s_mov_b64 s[22:23], 0
	global_store_dwordx4 v[34:35], v[36:39], off

; __device__ __forceinline__ float fast_sigmoid(float v) { return __builtin_amdgcn_rcpf(1.0f + __builtin_amdgcn_exp2f(-v * LOG2E)); }
; __device__ __forceinline__ u32x4 pack8(f32x4 a, f32x4 b) { u32x4 w; w.x = cvt_pk_bf16(a[0], a[1]); w.y = cvt_pk_bf16(a[2], a[3]); w.z = cvt_pk_bf16(b[0], b[1]); w.w = cvt_pk_bf16(b[2], b[3]); return w; }
;     __device__ __forceinline__ void operator()(Acc& acc, const Unit& u, int wr, int wc, int fr, int fq) const {
;     ...
;         for (int ai = 0; ai < 2; ++ai)
; #pragma unroll
;             for (int m = 0; m < 4; ++m) { bf16* rowp = base + (size_t)ai * sA + (size_t)(m >> 1) * sM2 + (size_t)(m & 1) * sM1;
; #pragma unroll
;                 for (int bj = 0; bj < 2; ++bj) { f32x4 v0 = acc[ai][bj][m][0] + bv[bj][0], v1 = acc[ai][bj][m][1] + bv[bj][1];
;                     if (sig) {
; #pragma unroll
;                         for (int e = 0; e < 4; ++e) { v0[e] = fast_sigmoid(v0[e]); v1[e] = fast_sigmoid(v1[e]); }
;                         *(u32x2*)(rowp + (size_t)bj * sB) = (u32x2){pack_gate4(v0), pack_gate4(v1)}; }
;                     else *(u32x4*)(rowp + (size_t)bj * sB) = pack8(v0, v1); } }
.LBB0_325:
	s_and_b64 vcc, exec, s[70:71]
	s_mov_b64 s[22:23], -1
	s_cbranch_vccnz .LBB0_327
	v_readlane_b32 s22, v254, 3
	v_readlane_b32 s23, v254, 4
	s_mov_b32 s17, s23
	s_lshl_b32 s22, s15, 1
	v_writelane_b32 v254, s16, 3
	v_cvt_pk_bf16_f32 v26, v22, v23
	v_cvt_pk_bf16_f32 v27, v24, v25
	v_cvt_pk_bf16_f32 v28, v18, v19
	v_cvt_pk_bf16_f32 v29, v20, v21
	v_writelane_b32 v254, s17, 4
	v_lshl_add_u64 v[30:31], v[34:35], 0, s[22:23]
	s_mov_b64 s[22:23], 0
	global_store_dwordx4 v[30:31], v[26:29], off

; __device__ __forceinline__ float fast_sigmoid(float v) { return __builtin_amdgcn_rcpf(1.0f + __builtin_amdgcn_exp2f(-v * LOG2E)); }
; __device__ __forceinline__ u32x4 pack8(f32x4 a, f32x4 b) { u32x4 w; w.x = cvt_pk_bf16(a[0], a[1]); w.y = cvt_pk_bf16(a[2], a[3]); w.z = cvt_pk_bf16(b[0], b[1]); w.w = cvt_pk_bf16(b[2], b[3]); return w; }
;     __device__ __forceinline__ void operator()(Acc& acc, const Unit& u, int wr, int wc, int fr, int fq) const {
;     ...
;         for (int ai = 0; ai < 2; ++ai)
; #pragma unroll
;             for (int m = 0; m < 4; ++m) { bf16* rowp = base + (size_t)ai * sA + (size_t)(m >> 1) * sM2 + (size_t)(m & 1) * sM1;
; #pragma unroll
;                 for (int bj = 0; bj < 2; ++bj) { f32x4 v0 = acc[ai][bj][m][0] + bv[bj][0], v1 = acc[ai][bj][m][1] + bv[bj][1];
;                     if (sig) {
; #pragma unroll
;                         for (int e = 0; e < 4; ++e) { v0[e] = fast_sigmoid(v0[e]); v1[e] = fast_sigmoid(v1[e]); }
;                         *(u32x2*)(rowp + (size_t)bj * sB) = (u32x2){pack_gate4(v0), pack_gate4(v1)}; }
;                     else *(u32x4*)(rowp + (size_t)bj * sB) = pack8(v0, v1); } }
.LBB0_329:
	v_lshl_add_u64 v[18:19], s[2:3], 1, v[34:35]
	s_and_b64 vcc, exec, s[70:71]
	s_mov_b64 s[2:3], -1
	s_cbranch_vccnz .LBB0_331
	v_cvt_pk_bf16_f32 v20, v14, v15
	v_cvt_pk_bf16_f32 v21, v16, v17
	v_cvt_pk_bf16_f32 v22, v10, v11
	v_cvt_pk_bf16_f32 v23, v12, v13
	s_mov_b64 s[2:3], 0
	global_store_dwordx4 v[18:19], v[20:23], off

; __device__ __forceinline__ float fast_sigmoid(float v) { return __builtin_amdgcn_rcpf(1.0f + __builtin_amdgcn_exp2f(-v * LOG2E)); }
; __device__ __forceinline__ u32x4 pack8(f32x4 a, f32x4 b) { u32x4 w; w.x = cvt_pk_bf16(a[0], a[1]); w.y = cvt_pk_bf16(a[2], a[3]); w.z = cvt_pk_bf16(b[0], b[1]); w.w = cvt_pk_bf16(b[2], b[3]); return w; }
;     __device__ __forceinline__ void operator()(Acc& acc, const Unit& u, int wr, int wc, int fr, int fq) const {
;     ...
;         for (int ai = 0; ai < 2; ++ai)
; #pragma unroll
;             for (int m = 0; m < 4; ++m) { bf16* rowp = base + (size_t)ai * sA + (size_t)(m >> 1) * sM2 + (size_t)(m & 1) * sM1;
; #pragma unroll
;                 for (int bj = 0; bj < 2; ++bj) { f32x4 v0 = acc[ai][bj][m][0] + bv[bj][0], v1 = acc[ai][bj][m][1] + bv[bj][1];
;                     if (sig) {
; #pragma unroll
;                         for (int e = 0; e < 4; ++e) { v0[e] = fast_sigmoid(v0[e]); v1[e] = fast_sigmoid(v1[e]); }
;                         *(u32x2*)(rowp + (size_t)bj * sB) = (u32x2){pack_gate4(v0), pack_gate4(v1)}; }
;                     else *(u32x4*)(rowp + (size_t)bj * sB) = pack8(v0, v1); } }
.LBB0_333:
	s_and_b64 vcc, exec, s[70:71]
	s_mov_b64 s[2:3], -1
	s_cbranch_vccnz .LBB0_336
	v_readlane_b32 s2, v254, 3
	v_readlane_b32 s3, v254, 4
	s_mov_b32 s23, s3
	s_lshl_b32 s22, s15, 1
	v_writelane_b32 v254, s2, 3
	v_cvt_pk_bf16_f32 v10, v6, v7
	v_cvt_pk_bf16_f32 v11, v8, v9
	v_cvt_pk_bf16_f32 v12, v2, v3
	v_cvt_pk_bf16_f32 v13, v4, v5
	v_writelane_b32 v254, s3, 4
	v_lshl_add_u64 v[14:15], v[18:19], 0, s[22:23]
	global_store_dwordx4 v[14:15], v[10:13], off
	s_cbranch_execz .LBB0_337
